# v19 = v13 with the steady-loop per-step barrier waiting vmcnt(3) only (no lgkmcnt(0): prefetched LDS fragments stay in flight across the barrier)
# baseline (speedup 1.0000x reference)
.LBB0_577:
	s_cmp_lt_u32 s90, 4
	s_cbranch_scc1 .Lstg_mid1
	s_waitcnt vmcnt(3)
	s_barrier
.Lstg_mid1:
	ds_read_b64_tr_b16 v[40:41], v167 offset:54272
	ds_read_b64_tr_b16 v[42:43], v167 offset:54784
	s_waitcnt lgkmcnt(6)
	v_mfma_f32_32x32x16_bf16 v[16:31], v[132:135], v[32:35], v[16:31]
	v_exp_f32_e32 v80, v80
	v_exp_f32_e32 v81, v81
	v_exp_f32_e32 v82, v82
	v_exp_f32_e32 v83, v83
	ds_read_b64_tr_b16 v[32:33], v167 offset:51200
	ds_read_b64_tr_b16 v[34:35], v167 offset:51712
	s_waitcnt lgkmcnt(6)
	v_mfma_f32_32x32x16_bf16 v[0:15], v[132:135], v[48:51], v[0:15]
	v_exp_f32_e32 v84, v84
	v_exp_f32_e32 v85, v85
	v_exp_f32_e32 v86, v86
	v_exp_f32_e32 v87, v87
	ds_read_b64_tr_b16 v[44:45], v167 offset:55296
	ds_read_b64_tr_b16 v[46:47], v167 offset:55808
	s_waitcnt lgkmcnt(6)
	v_mfma_f32_32x32x16_bf16 v[16:31], v[128:131], v[36:39], v[16:31]
	v_exp_f32_e32 v88, v88
	v_exp_f32_e32 v89, v89
	v_exp_f32_e32 v90, v90
	v_exp_f32_e32 v91, v91
	ds_read_b64_tr_b16 v[48:49], v167 offset:52224
	ds_read_b64_tr_b16 v[50:51], v167 offset:52736
	s_waitcnt lgkmcnt(6)
	v_mfma_f32_32x32x16_bf16 v[0:15], v[128:131], v[40:43], v[0:15]
	v_exp_f32_e32 v92, v92
	v_exp_f32_e32 v93, v93
	v_exp_f32_e32 v94, v94
	v_exp_f32_e32 v95, v95
	ds_read_b64_tr_b16 v[40:41], v167 offset:56320
	ds_read_b64_tr_b16 v[42:43], v167 offset:56832
	s_waitcnt lgkmcnt(6)
	v_mfma_f32_32x32x16_bf16 v[16:31], v[124:127], v[32:35], v[16:31]
	v_exp_f32_e32 v64, v64
	v_exp_f32_e32 v65, v65
	v_exp_f32_e32 v66, v66
	v_exp_f32_e32 v67, v67
	v_add_u32_e32 v142, s83, v179
	ds_read_b128 v[32:35], v142
	s_waitcnt lgkmcnt(5)
	v_mfma_f32_32x32x16_bf16 v[0:15], v[124:127], v[44:47], v[0:15]
	v_exp_f32_e32 v68, v68
	v_exp_f32_e32 v69, v69
	v_exp_f32_e32 v70, v70
	v_exp_f32_e32 v71, v71
	ds_read_b128 v[36:39], v142 offset:512
	s_waitcnt lgkmcnt(4)
	v_mfma_f32_32x32x16_bf16 v[16:31], v[120:123], v[48:51], v[16:31]
	v_exp_f32_e32 v72, v72
	v_exp_f32_e32 v73, v73
	v_exp_f32_e32 v74, v74
	v_exp_f32_e32 v75, v75
	ds_read_b128 v[136:139], v142 offset:2048
	s_waitcnt lgkmcnt(3)
	v_mfma_f32_32x32x16_bf16 v[0:15], v[120:123], v[40:43], v[0:15]
	v_exp_f32_e32 v76, v76
	v_exp_f32_e32 v77, v77
	v_exp_f32_e32 v78, v78
	v_exp_f32_e32 v79, v79
	s_cmp_lt_u32 s90, 4
	s_cbranch_scc0 .Lstg_end1
	s_waitcnt vmcnt(3)
	s_barrier

.Lstg_mid2:
	s_add_i32 s0, s83, 0x3000
	s_cmpk_lg_u32 s83, 0x9000
	s_cselect_b32 s82, s0, 0
	ds_read_b64_tr_b16 v[72:73], v141 offset:54272
	ds_read_b64_tr_b16 v[74:75], v141 offset:54784
	s_waitcnt lgkmcnt(6)
	v_mfma_f32_32x32x16_bf16 v[16:31], v[132:135], v[64:67], v[16:31]
	v_exp_f32_e32 v48, v48
	v_exp_f32_e32 v49, v49
	v_exp_f32_e32 v50, v50
	v_exp_f32_e32 v51, v51
	ds_read_b64_tr_b16 v[64:65], v141 offset:51200
	ds_read_b64_tr_b16 v[66:67], v141 offset:51712
	s_waitcnt lgkmcnt(6)
	v_mfma_f32_32x32x16_bf16 v[0:15], v[132:135], v[80:83], v[0:15]
	v_exp_f32_e32 v52, v52
	v_exp_f32_e32 v53, v53
	v_exp_f32_e32 v54, v54
	v_exp_f32_e32 v55, v55
	s_add_i32 s0, s79, 0x2000
	s_cmpk_lg_i32 s79, 0x4000
	s_cselect_b32 s0, s0, 0xe800
	s_cmpk_lg_u32 s79, 0xe800
	s_cselect_b32 s84, s0, 0
	ds_read_b64_tr_b16 v[76:77], v141 offset:55296
	ds_read_b64_tr_b16 v[78:79], v141 offset:55808
	s_waitcnt lgkmcnt(6)
	v_mfma_f32_32x32x16_bf16 v[16:31], v[128:131], v[68:71], v[16:31]
	v_exp_f32_e32 v56, v56
	v_exp_f32_e32 v57, v57
	v_exp_f32_e32 v58, v58
	v_exp_f32_e32 v59, v59
	s_add_i32 s0, s82, 0x3000
	s_cmpk_lg_u32 s82, 0x9000
	s_cselect_b32 s85, s0, 0
	ds_read_b64_tr_b16 v[68:69], v141 offset:52224
	ds_read_b64_tr_b16 v[70:71], v141 offset:52736
	s_waitcnt lgkmcnt(6)
	v_mfma_f32_32x32x16_bf16 v[0:15], v[128:131], v[72:75], v[0:15]
	v_exp_f32_e32 v60, v60
	v_exp_f32_e32 v61, v61
	v_exp_f32_e32 v62, v62
	v_exp_f32_e32 v63, v63
	s_add_u32 s68, s68, 0x30000
	s_addc_u32 s69, s69, 0
	ds_read_b64_tr_b16 v[72:73], v141 offset:56320
	ds_read_b64_tr_b16 v[74:75], v141 offset:56832
	s_waitcnt lgkmcnt(6)
	v_mfma_f32_32x32x16_bf16 v[16:31], v[124:127], v[64:67], v[16:31]
	v_exp_f32_e32 v32, v32
	v_exp_f32_e32 v33, v33
	v_exp_f32_e32 v34, v34
	v_exp_f32_e32 v35, v35
	s_add_u32 s48, s48, 0x48000
	s_addc_u32 s49, s49, 0
	v_add_u32_e32 v64, s82, v179
	ds_read_b128 v[80:83], v64
	s_waitcnt lgkmcnt(5)
	v_mfma_f32_32x32x16_bf16 v[0:15], v[124:127], v[76:79], v[0:15]
	v_exp_f32_e32 v36, v36
	v_exp_f32_e32 v37, v37
	v_exp_f32_e32 v38, v38
	v_exp_f32_e32 v39, v39
	s_add_u32 s8, s8, 0x2000
	s_addc_u32 s9, s9, 0
	ds_read_b128 v[136:139], v64 offset:512
	s_waitcnt lgkmcnt(4)
	v_mfma_f32_32x32x16_bf16 v[16:31], v[120:123], v[68:71], v[16:31]
	v_exp_f32_e32 v40, v40
	v_exp_f32_e32 v41, v41
	v_exp_f32_e32 v42, v42
	v_exp_f32_e32 v43, v43
	s_add_i32 s0, s87, 2
	ds_read_b128 v[140:143], v64 offset:2048
	s_waitcnt lgkmcnt(3)
	v_mfma_f32_32x32x16_bf16 v[0:15], v[120:123], v[72:75], v[0:15]
	v_exp_f32_e32 v44, v44
	v_exp_f32_e32 v45, v45
	v_exp_f32_e32 v46, v46
	v_exp_f32_e32 v47, v47
	s_cmp_lt_u32 s90, 4
	s_cbranch_scc0 .Lstg_end2
	s_waitcnt vmcnt(3)
	s_barrier
